# latent attention: partial-softmax block (row-max chain, scale, 16 exps) hoisted out of the barrier-to-barrier window into the PV-section MFMA gaps (dependency-checked list schedule, 5 temp VGPRs)
# speedup vs baseline: 1.0008x; 1.0008x over previous
.LBB0_709:
	s_add_i32 s20, s85, -3
	ds_read_b128 v[64:67], v204 offset:49152
	ds_read_b128 v[68:71], v204 offset:57344
	ds_read_b128 v[178:181], v207 offset:49152
	ds_read_b128 v[182:185], v207 offset:57344
	v_exp_f32_e32 v144, v158
	v_exp_f32_e32 v158, v159
	s_waitcnt lgkmcnt(3)
	v_mfma_f32_32x32x16_bf16 v[80:95], v[64:67], v[124:127], 0
	v_exp_f32_e32 v159, v160
	v_add_f32_e32 v160, 0, v216
	v_add_f32_e32 v160, v230, v160
	v_add_f32_e32 v160, v174, v160
	v_add_f32_e32 v160, v219, v160
	v_add_f32_e32 v160, v173, v160
	v_add_f32_e32 v160, v175, v160
	s_waitcnt lgkmcnt(2)
	v_mfma_f32_32x32x16_bf16 v[64:79], v[68:71], v[124:127], 0
	v_add_f32_e32 v160, v163, v160
	v_add_f32_e32 v160, v172, v160
	v_add_f32_e32 v160, v164, v160
	v_add_f32_e32 v160, v171, v160
	v_add_f32_e32 v160, v165, v160
	v_add_f32_e32 v160, v170, v160
	v_add_f32_e32 v160, v166, v160
	s_waitcnt lgkmcnt(1)
	v_mfma_f32_32x32x16_bf16 v[80:95], v[178:181], v[120:123], v[80:95]
	v_add_f32_e32 v160, v169, v160
	v_exp_f32_e32 v156, v156
	v_add_f32_e32 v160, v145, v160
	v_exp_f32_e32 v157, v157
	v_add_f32_e32 v160, v167, v160
	v_exp_f32_e32 v150, v150
	v_add_f32_e32 v160, v144, v160
	s_waitcnt lgkmcnt(0)
	v_mfma_f32_32x32x16_bf16 v[64:79], v[182:185], v[120:123], v[64:79]
	ds_read_b128 v[178:181], v209 offset:49152
	ds_read_b128 v[182:185], v209 offset:57344
	v_exp_f32_e32 v151, v151
	v_add_f32_e32 v160, v158, v160
	v_exp_f32_e32 v148, v148
	v_add_f32_e32 v160, v156, v160
	v_exp_f32_e32 v149, v149
	v_add_f32_e32 v160, v157, v160
	s_waitcnt lgkmcnt(1)
	v_mfma_f32_32x32x16_bf16 v[80:95], v[178:181], v[116:119], v[80:95]
	v_exp_f32_e32 v146, v146
	v_add_f32_e32 v160, v150, v160
	v_exp_f32_e32 v147, v147
	v_add_f32_e32 v160, v151, v160
	v_add_f32_e32 v160, v148, v160
	v_add_f32_e32 v160, v149, v160
	v_exp_f32_e32 v154, v154
	s_waitcnt lgkmcnt(0)
	v_mfma_f32_32x32x16_bf16 v[64:79], v[182:185], v[116:119], v[64:79]
	ds_read_b128 v[178:181], v205 offset:49152
	ds_read_b128 v[182:185], v205 offset:57344
	v_add_f32_e32 v160, v146, v160
	v_exp_f32_e32 v155, v155
	v_add_f32_e32 v160, v147, v160
	v_exp_f32_e32 v152, v152
	v_add_f32_e32 v160, v159, v160
	v_exp_f32_e32 v153, v153
	s_waitcnt lgkmcnt(1)
	v_mfma_f32_32x32x16_bf16 v[80:95], v[178:181], v[112:115], v[80:95]
	s_waitcnt lgkmcnt(0)
	v_mfma_f32_32x32x16_bf16 v[64:79], v[182:185], v[112:115], v[64:79]
	ds_read_b128 v[178:181], v206 offset:49152
	ds_read_b128 v[182:185], v206 offset:57344
	s_waitcnt lgkmcnt(1)
	v_mfma_f32_32x32x16_bf16 v[80:95], v[178:181], v[108:111], v[80:95]
	s_waitcnt lgkmcnt(0)
	v_mfma_f32_32x32x16_bf16 v[64:79], v[182:185], v[108:111], v[64:79]
	ds_read_b128 v[178:181], v208 offset:49152
	ds_read_b128 v[182:185], v208 offset:57344
	s_waitcnt lgkmcnt(1)
	v_mfma_f32_32x32x16_bf16 v[80:95], v[178:181], v[104:107], v[80:95]
	s_waitcnt lgkmcnt(0)
	v_mfma_f32_32x32x16_bf16 v[64:79], v[182:185], v[104:107], v[64:79]
	ds_read_b128 v[178:181], v210 offset:49152
	ds_read_b128 v[182:185], v210 offset:57344
	s_waitcnt lgkmcnt(1)
	v_mfma_f32_32x32x16_bf16 v[80:95], v[178:181], v[100:103], v[80:95]
	s_waitcnt lgkmcnt(0)
	v_mfma_f32_32x32x16_bf16 v[64:79], v[182:185], v[100:103], v[64:79]
	ds_read_b128 v[178:181], v211 offset:49152
	ds_read_b128 v[182:185], v211 offset:57344
	s_waitcnt lgkmcnt(1)
	v_mfma_f32_32x32x16_bf16 v[80:95], v[178:181], v[96:99], v[80:95]
	v_exp_f32_e32 v179, v161
	s_nop 0
	v_add_f32_e32 v160, v179, v160
	v_add_f32_e32 v160, v154, v160
	v_add_f32_e32 v160, v155, v160
	s_waitcnt lgkmcnt(0)
	v_mfma_f32_32x32x16_bf16 v[64:79], v[182:185], v[96:99], v[64:79]
	v_add_f32_e32 v160, v152, v160
	v_add_f32_e32 v213, v153, v160
	v_mov_b32_e32 v214, v213
	v_cvt_pk_bf16_f32 v160, v216, v230
	v_cvt_pk_bf16_f32 v161, v174, v219
	v_cvt_pk_bf16_f32 v162, v173, v175
	s_nop 1
	v_permlane32_swap_b32_e32 v213, v214
	v_cvt_pk_bf16_f32 v163, v163, v172
	v_permlane32_swap_b32_e32 v160, v162
	v_cvt_pk_bf16_f32 v164, v164, v171
	v_cvt_pk_bf16_f32 v165, v165, v170
	v_cvt_pk_bf16_f32 v166, v166, v169
	v_cvt_pk_bf16_f32 v167, v145, v167
	v_cvt_pk_bf16_f32 v170, v144, v158
	v_cvt_pk_bf16_f32 v171, v156, v157
	v_cvt_pk_bf16_f32 v172, v150, v151
	v_cvt_pk_bf16_f32 v173, v148, v149
	v_cvt_pk_bf16_f32 v178, v146, v147
	v_cvt_pk_bf16_f32 v179, v159, v179
	v_cvt_pk_bf16_f32 v180, v154, v155
	v_cvt_pk_bf16_f32 v181, v152, v153
	v_permlane32_swap_b32_e32 v161, v163
	v_permlane32_swap_b32_e32 v164, v166
	v_permlane32_swap_b32_e32 v165, v167
	v_permlane32_swap_b32_e32 v170, v172
	v_permlane32_swap_b32_e32 v171, v173
	v_permlane32_swap_b32_e32 v178, v180
	v_permlane32_swap_b32_e32 v179, v181
	s_cmp_lt_u32 s20, 6
	s_cselect_b64 s[4:5], -1, 0
	s_and_b64 s[18:19], s[4:5], exec
	s_cselect_b32 s16, 0, -8
	s_add_i32 s16, s16, s85
	s_add_i32 s16, s16, -1
	s_and_b64 s[4:5], s[4:5], exec
	s_cselect_b32 s19, s49, s43
	s_cselect_b32 s18, s48, s36
	s_cselect_b32 s21, s57, s52
	s_cselect_b32 s22, s56, s44
	s_lshl_b64 s[4:5], s[16:17], 16
	s_add_u32 s18, s18, s4
	s_addc_u32 s19, s19, s5
	s_add_u32 s4, s22, s4
	s_addc_u32 s5, s21, s5
	global_load_dwordx4 v[144:147], v222, s[4:5]
	global_load_dwordx4 v[148:151], v243, s[4:5]
	global_load_dwordx4 v[152:155], v222, s[18:19]
	global_load_dwordx4 v[156:159], v243, s[18:19]
	ds_read_b64_tr_b16 v[182:183], v199 offset:0
	ds_read_b64_tr_b16 v[184:185], v199 offset:0x800
	ds_read_b64_tr_b16 v[216:217], v199 offset:0x1000
	ds_read_b64_tr_b16 v[218:219], v199 offset:0x1800
	ds_read_b64_tr_b16 v[230:231], v199 offset:0x2000
	ds_read_b64_tr_b16 v[232:233], v199 offset:0x2800
	ds_read_b64_tr_b16 v[234:235], v199 offset:0x3000
	ds_read_b64_tr_b16 v[236:237], v199 offset:0x3800
	s_waitcnt lgkmcnt(0)
	s_nop 0
	v_mfma_f32_32x32x16_bf16 v[0:15], v[160:163], v[182:185], v[0:15]
	v_max_f32_e32 v192, v81, v81
	v_max_f32_e32 v193, v80, v80
	v_max_f32_e32 v192, v193, v192
	v_max3_f32 v192, v192, v82, v83
	v_max3_f32 v192, v192, v84, v85
	v_max3_f32 v192, v192, v86, v87
	ds_read_b64_tr_b16 v[182:183], v199 offset:0x200
	ds_read_b64_tr_b16 v[184:185], v199 offset:0xa00
	v_mfma_f32_32x32x16_bf16 v[0:15], v[164:167], v[216:219], v[0:15]
	v_max3_f32 v192, v192, v88, v89
	v_max3_f32 v192, v192, v90, v91
	v_max3_f32 v192, v192, v92, v93
	v_max3_f32 v192, v192, v94, v95
	v_max3_f32 v192, v192, v64, v65
	v_max3_f32 v192, v192, v66, v67
	ds_read_b64_tr_b16 v[216:217], v199 offset:0x1200
	ds_read_b64_tr_b16 v[218:219], v199 offset:0x1a00
	v_mfma_f32_32x32x16_bf16 v[0:15], v[170:173], v[230:233], v[0:15]
	v_max3_f32 v192, v192, v68, v69
	v_max3_f32 v192, v192, v70, v71
	v_max3_f32 v192, v192, v72, v73
	v_max3_f32 v192, v192, v74, v75
	v_max3_f32 v192, v192, v76, v77
	v_max3_f32 v192, v192, v78, v79
	ds_read_b64_tr_b16 v[230:231], v199 offset:0x2200
	ds_read_b64_tr_b16 v[232:233], v199 offset:0x2a00
	v_mfma_f32_32x32x16_bf16 v[0:15], v[178:181], v[234:237], v[0:15]
	v_mov_b32_e32 v193, v192
	s_nop 1
	v_permlane32_swap_b32_e32 v192, v193
	v_max_f32_e32 v193, v193, v193
	v_max_f32_e32 v192, v192, v192
	v_max_f32_e32 v192, v192, v193
	v_sub_f32_e32 v193, v192, v168
	ds_read_b64_tr_b16 v[234:235], v199 offset:0x3200
	ds_read_b64_tr_b16 v[236:237], v199 offset:0x3a00
	s_waitcnt lgkmcnt(0)
	v_mfma_f32_32x32x16_bf16 v[48:63], v[160:163], v[182:185], v[48:63]
	v_cmp_ge_f32_e32 vcc, s14, v193
	v_max_f32_e32 v193, v168, v168
	v_max_f32_e32 v192, v193, v192
	v_sub_f32_e32 v193, v168, v192
	v_mul_f32_e32 v193, 0x3e0293ee, v193
	v_exp_f32_e32 v193, v193
	ds_read_b64_tr_b16 v[182:183], v199 offset:0x400
	ds_read_b64_tr_b16 v[184:185], v199 offset:0xc00
	v_mfma_f32_32x32x16_bf16 v[48:63], v[164:167], v[216:219], v[48:63]
	s_cmp_eq_u64 vcc, exec
	s_cselect_b64 s[4:5], -1, 0
	v_cndmask_b32_e64 v215, v193, 1.0, s[4:5]
	v_cndmask_b32_e64 v194, v192, v168, s[4:5]
	v_mul_f32_e32 v195, 0xbe0293ee, v194
	v_fmamk_f32 v80, v80, 0x3e0293ee, v195
	v_fmamk_f32 v81, v81, 0x3e0293ee, v195
	ds_read_b64_tr_b16 v[216:217], v199 offset:0x1400
	ds_read_b64_tr_b16 v[218:219], v199 offset:0x1c00
	v_mfma_f32_32x32x16_bf16 v[48:63], v[170:173], v[230:233], v[48:63]
	v_fmamk_f32 v82, v82, 0x3e0293ee, v195
	v_fmamk_f32 v83, v83, 0x3e0293ee, v195
	v_fmamk_f32 v84, v84, 0x3e0293ee, v195
	v_fmamk_f32 v85, v85, 0x3e0293ee, v195
	v_fmamk_f32 v86, v86, 0x3e0293ee, v195
	v_fmamk_f32 v87, v87, 0x3e0293ee, v195
	ds_read_b64_tr_b16 v[230:231], v199 offset:0x2400
	ds_read_b64_tr_b16 v[232:233], v199 offset:0x2c00
	v_mfma_f32_32x32x16_bf16 v[48:63], v[178:181], v[234:237], v[48:63]
	v_fmamk_f32 v88, v88, 0x3e0293ee, v195
	v_fmamk_f32 v89, v89, 0x3e0293ee, v195
	v_fmamk_f32 v90, v90, 0x3e0293ee, v195
	v_fmamk_f32 v91, v91, 0x3e0293ee, v195
	v_fmamk_f32 v92, v92, 0x3e0293ee, v195
	v_fmamk_f32 v93, v93, 0x3e0293ee, v195
	ds_read_b64_tr_b16 v[234:235], v199 offset:0x3400
	ds_read_b64_tr_b16 v[236:237], v199 offset:0x3c00
	s_waitcnt lgkmcnt(0)
	v_mfma_f32_32x32x16_bf16 v[32:47], v[160:163], v[182:185], v[32:47]
	v_fmamk_f32 v94, v94, 0x3e0293ee, v195
	v_fmamk_f32 v95, v95, 0x3e0293ee, v195
	v_exp_f32_e32 v175, v81
	v_exp_f32_e32 v174, v83
	v_exp_f32_e32 v169, v93
	v_exp_f32_e32 v168, v95
	ds_read_b64_tr_b16 v[182:183], v199 offset:0x600
	ds_read_b64_tr_b16 v[184:185], v199 offset:0xe00
	v_mfma_f32_32x32x16_bf16 v[32:47], v[164:167], v[216:219], v[32:47]
	v_fmamk_f32 v238, v66, 0x3e0293ee, v195
	v_fmamk_f32 v239, v67, 0x3e0293ee, v195
	v_fmamk_f32 v240, v68, 0x3e0293ee, v195
	v_fmamk_f32 v241, v77, 0x3e0293ee, v195
	v_fmamk_f32 v242, v78, 0x3e0293ee, v195
	ds_read_b64_tr_b16 v[216:217], v199 offset:0x1600
	ds_read_b64_tr_b16 v[218:219], v199 offset:0x1e00
	v_mfma_f32_32x32x16_bf16 v[32:47], v[170:173], v[230:233], v[32:47]
	ds_read_b64_tr_b16 v[230:231], v199 offset:0x2600
	ds_read_b64_tr_b16 v[232:233], v199 offset:0x2e00
	v_mfma_f32_32x32x16_bf16 v[32:47], v[178:181], v[234:237], v[32:47]
	ds_read_b64_tr_b16 v[234:235], v199 offset:0x3600
	ds_read_b64_tr_b16 v[236:237], v199 offset:0x3e00
	s_waitcnt lgkmcnt(0)
	v_mfma_f32_32x32x16_bf16 v[16:31], v[160:163], v[182:185], v[16:31]
	v_exp_f32_e32 v160, v80
	v_exp_f32_e32 v161, v82
	v_exp_f32_e32 v162, v84
	v_exp_f32_e32 v163, v86
	v_mfma_f32_32x32x16_bf16 v[16:31], v[164:167], v[216:219], v[16:31]
	v_exp_f32_e32 v164, v88
	v_exp_f32_e32 v165, v90
	v_exp_f32_e32 v166, v92
	v_exp_f32_e32 v167, v94
	v_fmamk_f32 v219, v69, 0x3e0293ee, v195
	v_fmamk_f32 v218, v76, 0x3e0293ee, v195
	v_mov_b32_e32 v216, v194
	v_mfma_f32_32x32x16_bf16 v[16:31], v[170:173], v[230:233], v[16:31]
	v_exp_f32_e32 v173, v85
	v_exp_f32_e32 v172, v87
	v_exp_f32_e32 v171, v89
	v_exp_f32_e32 v170, v91
	v_fmamk_f32 v230, v70, 0x3e0293ee, v195
	v_fmamk_f32 v231, v71, 0x3e0293ee, v195
	v_fmamk_f32 v232, v72, 0x3e0293ee, v195
	v_mfma_f32_32x32x16_bf16 v[16:31], v[178:181], v[234:237], v[16:31]
	v_fmamk_f32 v236, v64, 0x3e0293ee, v195
	v_fmamk_f32 v237, v65, 0x3e0293ee, v195
	v_fmamk_f32 v233, v73, 0x3e0293ee, v195
	v_fmamk_f32 v234, v74, 0x3e0293ee, v195
	v_fmamk_f32 v235, v75, 0x3e0293ee, v195
	v_mov_b32_e32 v217, v195
	v_fmac_f32_e32 v217, 0x3e0293ee, v79
	s_barrier
	s_waitcnt vmcnt(4)
	v_cmp_gt_f32_e32 vcc, 1.0, v215
	s_waitcnt vmcnt(4)
	ds_write_b128 v200, v[128:131]
	ds_write_b128 v201, v[132:135]
	ds_write_b128 v202, v[136:139] offset:32768
	ds_write_b128 v203, v[140:143] offset:32768
	s_cbranch_vccz .LBB0_713
	s_and_saveexec_b64 s[18:19], s[2:3]
	ds_write_b32 v189, v215 offset:128
	s_or_b64 exec, exec, s[18:19]
	s_waitcnt lgkmcnt(0)
	v_add_u32_e32 v80, v191, v190
	ds_read_b128 v[64:67], v80 offset:224
	ds_read_b128 v[68:71], v80 offset:192
	ds_read_b128 v[72:75], v80 offset:160
	ds_read_b128 v[76:79], v80 offset:128
	s_waitcnt lgkmcnt(3)
	v_pk_mul_f32 v[12:13], v[12:13], v[64:65]
	s_waitcnt lgkmcnt(2)
	v_pk_mul_f32 v[8:9], v[8:9], v[68:69]
	s_waitcnt lgkmcnt(1)
	v_pk_mul_f32 v[4:5], v[4:5], v[72:73]
	v_pk_mul_f32 v[14:15], v[14:15], v[66:67]
	v_pk_mul_f32 v[10:11], v[10:11], v[70:71]
	v_pk_mul_f32 v[6:7], v[6:7], v[74:75]
	s_waitcnt lgkmcnt(0)
	v_pk_mul_f32 v[2:3], v[2:3], v[78:79]
	v_pk_mul_f32 v[0:1], v[0:1], v[76:77]
	v_pk_mul_f32 v[60:61], v[60:61], v[64:65]
	v_pk_mul_f32 v[56:57], v[56:57], v[68:69]
	v_pk_mul_f32 v[52:53], v[52:53], v[72:73]
	v_pk_mul_f32 v[62:63], v[62:63], v[66:67]
	v_pk_mul_f32 v[58:59], v[58:59], v[70:71]
	v_pk_mul_f32 v[54:55], v[54:55], v[74:75]
	v_pk_mul_f32 v[50:51], v[50:51], v[78:79]
	v_pk_mul_f32 v[48:49], v[48:49], v[76:77]
	v_pk_mul_f32 v[44:45], v[44:45], v[64:65]
	v_pk_mul_f32 v[40:41], v[40:41], v[68:69]
	v_pk_mul_f32 v[36:37], v[36:37], v[72:73]
	v_pk_mul_f32 v[46:47], v[46:47], v[66:67]
	v_pk_mul_f32 v[42:43], v[42:43], v[70:71]
	v_pk_mul_f32 v[38:39], v[38:39], v[74:75]
	v_pk_mul_f32 v[34:35], v[34:35], v[78:79]
	v_pk_mul_f32 v[32:33], v[32:33], v[76:77]
	v_pk_mul_f32 v[28:29], v[28:29], v[64:65]
	v_pk_mul_f32 v[24:25], v[24:25], v[68:69]
	v_pk_mul_f32 v[20:21], v[20:21], v[72:73]
	v_pk_mul_f32 v[30:31], v[30:31], v[66:67]
	v_pk_mul_f32 v[26:27], v[26:27], v[70:71]
	v_pk_mul_f32 v[22:23], v[22:23], v[74:75]
	v_pk_mul_f32 v[18:19], v[18:19], v[78:79]
	v_pk_mul_f32 v[16:17], v[16:17], v[76:77]
.LBB0_713:
	s_waitcnt lgkmcnt(0)
	s_barrier
	ds_read_b128 v[64:67], v204 offset:32768
	ds_read_b128 v[68:71], v204 offset:40960
	ds_read_b128 v[178:181], v207 offset:32768
	ds_read_b128 v[182:185], v207 offset:40960
	v_exp_f32_e32 v186, v232
	v_exp_f32_e32 v232, v217
	s_waitcnt lgkmcnt(3)
	v_mfma_f32_32x32x16_bf16 v[80:95], v[64:67], v[124:127], 0
	v_add_f32_e32 v217, 0, v160
	v_add_f32_e32 v217, v175, v217
	v_add_f32_e32 v217, v161, v217
	v_add_f32_e32 v217, v174, v217
	v_add_f32_e32 v217, v162, v217
	v_add_f32_e32 v217, v173, v217
	v_add_f32_e32 v217, v163, v217
	s_waitcnt lgkmcnt(2)
	v_mfma_f32_32x32x16_bf16 v[64:79], v[68:71], v[124:127], 0
	v_add_f32_e32 v217, v172, v217
	v_add_f32_e32 v217, v164, v217
	v_add_f32_e32 v217, v171, v217
	v_add_f32_e32 v217, v165, v217
	v_add_f32_e32 v217, v170, v217
	v_add_f32_e32 v217, v166, v217
	v_add_f32_e32 v217, v169, v217
	s_waitcnt lgkmcnt(1)
	v_mfma_f32_32x32x16_bf16 v[80:95], v[178:181], v[120:123], v[80:95]
	v_add_f32_e32 v217, v167, v217
	v_add_f32_e32 v217, v168, v217
	v_exp_f32_e32 v187, v233
	v_exp_f32_e32 v224, v235
	v_exp_f32_e32 v225, v218
	s_waitcnt lgkmcnt(0)
	v_mfma_f32_32x32x16_bf16 v[64:79], v[182:185], v[120:123], v[64:79]
	ds_read_b128 v[178:181], v209 offset:32768
	ds_read_b128 v[182:185], v209 offset:40960
	s_waitcnt lgkmcnt(1)
	v_mfma_f32_32x32x16_bf16 v[80:95], v[178:181], v[116:119], v[80:95]
	s_waitcnt lgkmcnt(0)
	v_mfma_f32_32x32x16_bf16 v[64:79], v[182:185], v[116:119], v[64:79]
	ds_read_b128 v[178:181], v205 offset:32768
	ds_read_b128 v[182:185], v205 offset:40960
	s_waitcnt lgkmcnt(1)
	v_mfma_f32_32x32x16_bf16 v[80:95], v[178:181], v[112:115], v[80:95]
	s_waitcnt lgkmcnt(0)
	v_mfma_f32_32x32x16_bf16 v[64:79], v[182:185], v[112:115], v[64:79]
	ds_read_b128 v[178:181], v206 offset:32768
	ds_read_b128 v[182:185], v206 offset:40960
	s_waitcnt lgkmcnt(1)
	v_mfma_f32_32x32x16_bf16 v[80:95], v[178:181], v[108:111], v[80:95]
	s_waitcnt lgkmcnt(0)
	v_mfma_f32_32x32x16_bf16 v[64:79], v[182:185], v[108:111], v[64:79]
	ds_read_b128 v[178:181], v208 offset:32768
	ds_read_b128 v[182:185], v208 offset:40960
	s_waitcnt lgkmcnt(1)
	v_mfma_f32_32x32x16_bf16 v[80:95], v[178:181], v[104:107], v[80:95]
	s_waitcnt lgkmcnt(0)
	v_mfma_f32_32x32x16_bf16 v[64:79], v[182:185], v[104:107], v[64:79]
	ds_read_b128 v[178:181], v210 offset:32768
	ds_read_b128 v[182:185], v210 offset:40960
	s_waitcnt lgkmcnt(1)
	v_mfma_f32_32x32x16_bf16 v[80:95], v[178:181], v[100:103], v[80:95]
	s_waitcnt lgkmcnt(0)
	v_mfma_f32_32x32x16_bf16 v[64:79], v[182:185], v[100:103], v[64:79]
	ds_read_b128 v[178:181], v211 offset:32768
	ds_read_b128 v[182:185], v211 offset:40960
	v_cvt_pk_bf16_f32 v160, v160, v175
	v_cvt_pk_bf16_f32 v161, v161, v174
	v_cvt_pk_bf16_f32 v162, v162, v173
	v_cvt_pk_bf16_f32 v163, v163, v172
	v_cvt_pk_bf16_f32 v164, v164, v171
	v_cvt_pk_bf16_f32 v165, v165, v170
	s_waitcnt lgkmcnt(1)
	v_mfma_f32_32x32x16_bf16 v[80:95], v[178:181], v[96:99], v[80:95]
	v_exp_f32_e32 v178, v236
	v_exp_f32_e32 v179, v237
	v_exp_f32_e32 v180, v238
	v_exp_f32_e32 v181, v239
	v_add_f32_e32 v217, v178, v217
	v_add_f32_e32 v217, v179, v217
	v_add_f32_e32 v217, v180, v217
	s_waitcnt lgkmcnt(0)
	v_mfma_f32_32x32x16_bf16 v[64:79], v[182:185], v[96:99], v[64:79]
	v_exp_f32_e32 v182, v240
	v_exp_f32_e32 v183, v219
	v_exp_f32_e32 v184, v230
	v_exp_f32_e32 v185, v231
	v_add_f32_e32 v217, v181, v217
	v_add_f32_e32 v217, v182, v217
	v_add_f32_e32 v217, v183, v217
	v_exp_f32_e32 v219, v234
	v_add_f32_e32 v217, v184, v217
	v_add_f32_e32 v217, v185, v217
	v_add_f32_e32 v217, v186, v217
	v_exp_f32_e32 v230, v241
	v_add_f32_e32 v217, v187, v217
	v_exp_f32_e32 v231, v242
	v_add_f32_e32 v217, v219, v217
	v_add_f32_e32 v217, v224, v217
	v_add_f32_e32 v217, v225, v217
	v_add_f32_e32 v217, v230, v217
	v_add_f32_e32 v217, v231, v217
	v_add_f32_e32 v217, v232, v217
	v_mov_b32_e32 v218, v217
	v_cvt_pk_bf16_f32 v166, v166, v169
	v_cvt_pk_bf16_f32 v167, v167, v168
	v_cvt_pk_bf16_f32 v168, v178, v179
	v_cvt_pk_bf16_f32 v169, v180, v181
	v_cvt_pk_bf16_f32 v170, v182, v183
	v_cvt_pk_bf16_f32 v171, v184, v185
	v_cvt_pk_bf16_f32 v172, v186, v187
	v_cvt_pk_bf16_f32 v173, v219, v224
	v_cvt_pk_bf16_f32 v174, v225, v230
	v_cvt_pk_bf16_f32 v175, v231, v232
	s_nop 1
	v_permlane32_swap_b32_e32 v217, v218
	v_permlane32_swap_b32_e32 v160, v162
	v_permlane32_swap_b32_e32 v161, v163
	v_permlane32_swap_b32_e32 v164, v166
	v_permlane32_swap_b32_e32 v165, v167
	v_permlane32_swap_b32_e32 v168, v170
	v_permlane32_swap_b32_e32 v169, v171
	v_permlane32_swap_b32_e32 v172, v174
	v_permlane32_swap_b32_e32 v173, v175
	s_cmpk_gt_u32 s20, 0x44
	s_cbranch_scc1 .LBB0_715
	s_cmp_lt_u32 s20, 5
	s_cselect_b64 s[4:5], -1, 0
	s_and_b64 s[18:19], s[4:5], exec
	s_cselect_b32 s16, 0, -8
	s_add_i32 s16, s16, s85
	s_and_b64 s[4:5], s[4:5], exec
	s_cselect_b32 s19, s49, s43
	s_cselect_b32 s18, s48, s36
	s_cselect_b32 s21, s57, s52
	s_cselect_b32 s22, s56, s44
	s_lshl_b64 s[4:5], s[16:17], 16
	s_add_u32 s18, s18, s4
	s_addc_u32 s19, s19, s5
	s_add_u32 s4, s22, s4
	s_addc_u32 s5, s21, s5
	global_load_dwordx4 v[128:131], v222, s[4:5]
	global_load_dwordx4 v[132:135], v243, s[4:5]
	global_load_dwordx4 v[136:139], v222, s[18:19]
	global_load_dwordx4 v[140:143], v243, s[18:19]
.LBB0_715:
	ds_read_b64_tr_b16 v[178:179], v198 offset:0
	ds_read_b64_tr_b16 v[180:181], v198 offset:0x800
	ds_read_b64_tr_b16 v[182:183], v198 offset:0x1000
	ds_read_b64_tr_b16 v[184:185], v198 offset:0x1800
	ds_read_b64_tr_b16 v[230:231], v198 offset:0x2000
	ds_read_b64_tr_b16 v[232:233], v198 offset:0x2800
	ds_read_b64_tr_b16 v[234:235], v198 offset:0x3000
	ds_read_b64_tr_b16 v[236:237], v198 offset:0x3800
	s_waitcnt lgkmcnt(0)
	s_nop 0
	v_mfma_f32_32x32x16_bf16 v[0:15], v[160:163], v[178:181], v[0:15]
	v_max_f32_e32 v192, v81, v81
	v_max_f32_e32 v193, v80, v80
	v_max_f32_e32 v192, v193, v192
	v_max3_f32 v192, v192, v82, v83
	v_max3_f32 v192, v192, v84, v85
	ds_read_b64_tr_b16 v[178:179], v198 offset:0x200
	ds_read_b64_tr_b16 v[180:181], v198 offset:0xa00
	v_mfma_f32_32x32x16_bf16 v[0:15], v[164:167], v[182:185], v[0:15]
	v_max3_f32 v192, v192, v86, v87
	v_max3_f32 v192, v192, v88, v89
	v_max3_f32 v192, v192, v90, v91
	v_max3_f32 v192, v192, v92, v93
	v_max3_f32 v192, v192, v94, v95
	ds_read_b64_tr_b16 v[182:183], v198 offset:0x1200
	ds_read_b64_tr_b16 v[184:185], v198 offset:0x1a00
	v_mfma_f32_32x32x16_bf16 v[0:15], v[168:171], v[230:233], v[0:15]
	v_max3_f32 v192, v192, v64, v65
	v_max3_f32 v192, v192, v66, v67
	v_max3_f32 v192, v192, v68, v69
	v_max3_f32 v192, v192, v70, v71
	v_max3_f32 v192, v192, v72, v73
	ds_read_b64_tr_b16 v[230:231], v198 offset:0x2200
	ds_read_b64_tr_b16 v[232:233], v198 offset:0x2a00
	v_mfma_f32_32x32x16_bf16 v[0:15], v[172:175], v[234:237], v[0:15]
	v_max3_f32 v192, v192, v74, v75
	v_max3_f32 v192, v192, v76, v77
	v_max3_f32 v192, v192, v78, v79
	v_mov_b32_e32 v193, v192
	s_nop 1
	v_permlane32_swap_b32_e32 v192, v193
	ds_read_b64_tr_b16 v[234:235], v198 offset:0x3200
	ds_read_b64_tr_b16 v[236:237], v198 offset:0x3a00
	s_waitcnt lgkmcnt(0)
	v_mfma_f32_32x32x16_bf16 v[48:63], v[160:163], v[178:181], v[48:63]
	v_max_f32_e32 v193, v193, v193
	v_max_f32_e32 v192, v192, v192
	v_max_f32_e32 v192, v192, v193
	v_sub_f32_e32 v193, v192, v216
	v_cmp_ge_f32_e32 vcc, s14, v193
	ds_read_b64_tr_b16 v[178:179], v198 offset:0x400
	ds_read_b64_tr_b16 v[180:181], v198 offset:0xc00
	v_mfma_f32_32x32x16_bf16 v[48:63], v[164:167], v[182:185], v[48:63]
	v_max_f32_e32 v193, v216, v216
	v_max_f32_e32 v192, v193, v192
	v_sub_f32_e32 v193, v216, v192
	v_mul_f32_e32 v193, 0x3e0293ee, v193
	v_exp_f32_e32 v193, v193
	ds_read_b64_tr_b16 v[182:183], v198 offset:0x1400
	ds_read_b64_tr_b16 v[184:185], v198 offset:0x1c00
	v_mfma_f32_32x32x16_bf16 v[48:63], v[168:171], v[230:233], v[48:63]
	s_cmp_eq_u64 vcc, exec
	s_cselect_b64 s[4:5], -1, 0
	v_cndmask_b32_e64 v195, v192, v216, s[4:5]
	v_mul_f32_e32 v194, 0xbe0293ee, v195
	v_fmamk_f32 v94, v94, 0x3e0293ee, v194
	v_mov_b32_e32 v247, v194
	ds_read_b64_tr_b16 v[230:231], v198 offset:0x2400
	ds_read_b64_tr_b16 v[232:233], v198 offset:0x2c00
	v_mfma_f32_32x32x16_bf16 v[48:63], v[172:175], v[234:237], v[48:63]
	v_fmamk_f32 v80, v80, 0x3e0293ee, v194
	v_fmamk_f32 v81, v81, 0x3e0293ee, v194
	v_fmamk_f32 v82, v82, 0x3e0293ee, v194
	v_fmamk_f32 v83, v83, 0x3e0293ee, v194
	ds_read_b64_tr_b16 v[234:235], v198 offset:0x3400
	ds_read_b64_tr_b16 v[236:237], v198 offset:0x3c00
	s_waitcnt lgkmcnt(0)
	v_mfma_f32_32x32x16_bf16 v[32:47], v[160:163], v[178:181], v[32:47]
	v_fmamk_f32 v84, v84, 0x3e0293ee, v194
	v_fmamk_f32 v85, v85, 0x3e0293ee, v194
	v_fmamk_f32 v86, v86, 0x3e0293ee, v194
	v_fmamk_f32 v87, v87, 0x3e0293ee, v194
	ds_read_b64_tr_b16 v[178:179], v198 offset:0x600
	ds_read_b64_tr_b16 v[180:181], v198 offset:0xe00
	v_mfma_f32_32x32x16_bf16 v[32:47], v[164:167], v[182:185], v[32:47]
	v_fmamk_f32 v88, v88, 0x3e0293ee, v194
	v_fmamk_f32 v89, v89, 0x3e0293ee, v194
	v_fmamk_f32 v90, v90, 0x3e0293ee, v194
	v_fmamk_f32 v91, v91, 0x3e0293ee, v194
	ds_read_b64_tr_b16 v[182:183], v198 offset:0x1600
	ds_read_b64_tr_b16 v[184:185], v198 offset:0x1e00
	v_mfma_f32_32x32x16_bf16 v[32:47], v[168:171], v[230:233], v[32:47]
	v_fmamk_f32 v92, v92, 0x3e0293ee, v194
	v_fmamk_f32 v93, v93, 0x3e0293ee, v194
	v_fmac_f32_e32 v247, 0x3e0293ee, v95
	v_exp_f32_e32 v216, v80
	ds_read_b64_tr_b16 v[230:231], v198 offset:0x2600
	ds_read_b64_tr_b16 v[232:233], v198 offset:0x2e00
	v_mfma_f32_32x32x16_bf16 v[32:47], v[172:175], v[234:237], v[32:47]
	v_exp_f32_e32 v219, v83
	ds_read_b64_tr_b16 v[234:235], v198 offset:0x3600
	ds_read_b64_tr_b16 v[236:237], v198 offset:0x3e00
	s_waitcnt lgkmcnt(0)
	v_mfma_f32_32x32x16_bf16 v[16:31], v[160:163], v[178:181], v[16:31]
	v_cndmask_b32_e64 v162, v193, 1.0, s[4:5]
	v_exp_f32_e32 v163, v86
	v_mfma_f32_32x32x16_bf16 v[16:31], v[164:167], v[182:185], v[16:31]
	v_exp_f32_e32 v164, v88
	v_exp_f32_e32 v165, v90
	v_exp_f32_e32 v166, v92
	v_exp_f32_e32 v167, v247
	v_mfma_f32_32x32x16_bf16 v[16:31], v[168:171], v[230:233], v[16:31]
	v_mov_b32_e32 v168, v195
	v_exp_f32_e32 v230, v81
	v_exp_f32_e32 v171, v89
	v_exp_f32_e32 v170, v91
	v_exp_f32_e32 v169, v93
	v_mfma_f32_32x32x16_bf16 v[16:31], v[172:175], v[234:237], v[16:31]
	v_exp_f32_e32 v174, v82
	v_exp_f32_e32 v173, v84
	v_exp_f32_e32 v175, v85
	v_exp_f32_e32 v172, v87
	s_barrier
	s_waitcnt vmcnt(4)
	v_cmp_gt_f32_e32 vcc, 1.0, v162
	s_waitcnt vmcnt(3)
	ds_write_b128 v200, v[144:147] offset:16384
	s_waitcnt vmcnt(2)
	ds_write_b128 v201, v[148:151] offset:16384
	s_waitcnt vmcnt(1)
	ds_write_b128 v202, v[152:155] offset:49152
	s_waitcnt vmcnt(0)
	ds_write_b128 v203, v[156:159] offset:49152
	s_cbranch_vccz .LBB0_719
	s_and_saveexec_b64 s[18:19], s[2:3]
	ds_write_b32 v189, v162 offset:128
	s_or_b64 exec, exec, s[18:19]
	s_waitcnt lgkmcnt(0)
	v_add_u32_e32 v156, v191, v190
	ds_read_b128 v[144:147], v156 offset:224
	ds_read_b128 v[148:151], v156 offset:192
	ds_read_b128 v[152:155], v156 offset:160
	ds_read_b128 v[156:159], v156 offset:128
	s_waitcnt lgkmcnt(3)
	v_pk_mul_f32 v[12:13], v[12:13], v[144:145]
	s_waitcnt lgkmcnt(2)
	v_pk_mul_f32 v[8:9], v[8:9], v[148:149]
	s_waitcnt lgkmcnt(1)
	v_pk_mul_f32 v[4:5], v[4:5], v[152:153]
	v_pk_mul_f32 v[14:15], v[14:15], v[146:147]
	v_pk_mul_f32 v[10:11], v[10:11], v[150:151]
	v_pk_mul_f32 v[6:7], v[6:7], v[154:155]
	s_waitcnt lgkmcnt(0)
	v_pk_mul_f32 v[2:3], v[2:3], v[158:159]
	v_pk_mul_f32 v[0:1], v[0:1], v[156:157]
	v_pk_mul_f32 v[60:61], v[60:61], v[144:145]
	v_pk_mul_f32 v[56:57], v[56:57], v[148:149]
	v_pk_mul_f32 v[52:53], v[52:53], v[152:153]
	v_pk_mul_f32 v[62:63], v[62:63], v[146:147]
	v_pk_mul_f32 v[58:59], v[58:59], v[150:151]
	v_pk_mul_f32 v[54:55], v[54:55], v[154:155]
	v_pk_mul_f32 v[50:51], v[50:51], v[158:159]
	v_pk_mul_f32 v[48:49], v[48:49], v[156:157]
	v_pk_mul_f32 v[44:45], v[44:45], v[144:145]
	v_pk_mul_f32 v[40:41], v[40:41], v[148:149]
	v_pk_mul_f32 v[36:37], v[36:37], v[152:153]
	v_pk_mul_f32 v[46:47], v[46:47], v[146:147]
	v_pk_mul_f32 v[42:43], v[42:43], v[150:151]
	v_pk_mul_f32 v[38:39], v[38:39], v[154:155]
	v_pk_mul_f32 v[34:35], v[34:35], v[158:159]
	v_pk_mul_f32 v[32:33], v[32:33], v[156:157]
	v_pk_mul_f32 v[28:29], v[28:29], v[144:145]
	v_pk_mul_f32 v[24:25], v[24:25], v[148:149]
	v_pk_mul_f32 v[20:21], v[20:21], v[152:153]
	v_pk_mul_f32 v[30:31], v[30:31], v[146:147]
	v_pk_mul_f32 v[26:27], v[26:27], v[150:151]
	v_pk_mul_f32 v[22:23], v[22:23], v[154:155]
	v_pk_mul_f32 v[18:19], v[18:19], v[158:159]
	v_pk_mul_f32 v[16:17], v[16:17], v[156:157]
.LBB0_719:
	v_pk_fma_f32 v[158:159], v[64:65], s[88:89], v[194:195] op_sel_hi:[1,0,0]
	v_pk_fma_f32 v[156:157], v[66:67], s[88:89], v[194:195] op_sel_hi:[1,0,0]
	v_pk_fma_f32 v[150:151], v[68:69], s[88:89], v[194:195] op_sel_hi:[1,0,0]
	v_pk_fma_f32 v[148:149], v[70:71], s[88:89], v[194:195] op_sel_hi:[1,0,0]
	v_pk_fma_f32 v[146:147], v[72:73], s[88:89], v[194:195] op_sel_hi:[1,0,0]
	v_exp_f32_e32 v145, v94
	v_add_f32_e32 v64, v213, v214
	v_fmac_f32_e32 v64, v212, v197
	v_add_f32_e32 v197, v217, v218
	s_add_i32 s85, s85, 2
	v_pk_fma_f32 v[160:161], v[74:75], s[88:89], v[194:195] op_sel_hi:[1,0,0]
	v_pk_fma_f32 v[154:155], v[76:77], s[88:89], v[194:195] op_sel_hi:[1,0,0]
	v_pk_fma_f32 v[152:153], v[78:79], s[88:89], v[194:195] op_sel_hi:[1,0,0]
	v_fmac_f32_e32 v197, v64, v215
	s_cmpk_gt_u32 s20, 0x44
	s_waitcnt lgkmcnt(0)
	s_barrier
	s_cbranch_scc1 .LBB0_721
	v_mov_b32_e32 v212, v162
	s_branch .LBB0_709
